# baseline (speedup 1.0000x reference)
; DI int ltid() { int x = threadIdx.x; asm volatile("" : "+v"(x)); return x; }
; __global__ void __launch_bounds__(256, 2) trunk_fwd(Params p) {
;   __shared__ __attribute__((aligned(1024))) char smem[SM_TOTAL];
;   if (ltid() < 4) ((unsigned*)(smem + SM_BAR))[ltid()] = 0u;
;   __syncthreads();
_Z9trunk_fwd6Params:
	v_and_b32_e32 v222, 0x3ff, v0
	v_mov_b32_e32 v1, v222
	s_mov_b32 s43, s2
	s_cmpk_lt_u32 s2, 0x100
	s_cbranch_scc1 .Lprio_done
	s_setprio 1
.Lprio_done:
	s_mov_b64 s[56:57], s[0:1]
	s_nop 0
	v_cmp_gt_i32_e32 vcc, 4, v1
	s_and_saveexec_b64 s[0:1], vcc
	s_cbranch_execz .LBB0_2
	v_mov_b32_e32 v1, v222
	v_mov_b32_e32 v2, 0x12030
	v_lshl_add_u32 v1, v1, 2, v2
	v_mov_b32_e32 v2, 0
	ds_write_b32 v1, v2
